# in-proj epilogue stores (P rows, transposed copies, fp32 cache outputs) also write-through (sc1)
# baseline (speedup 1.0000x reference)
.LBB0_347:
	s_mul_hi_u32 s20, s19, 0xaaaaaaab
	s_lshr_b32 s20, s20, 1
	s_mul_i32 s20, s20, 0x24000
	s_waitcnt lgkmcnt(0)
	v_mfma_f32_16x16x32_bf16 v[82:85], v[26:29], v[22:25], v[82:85]
	v_add_u32_e32 v191, s13, v122
	s_mul_hi_u32 s23, s14, 0xaaaaaaab
	s_lshr_b32 s23, s23, 1
	v_mfma_f32_16x16x32_bf16 v[78:81], v[26:29], v[18:21], v[78:81]
	s_mul_i32 s23, s23, 0x24000
	v_subrev_u32_e32 v250, s23, v182
	v_subrev_u32_e32 v251, s23, v201
	v_mfma_f32_16x16x32_bf16 v[74:77], v[26:29], v[10:13], v[74:77]
	v_subrev_u32_e32 v252, s23, v202
	v_mfma_f32_16x16x32_bf16 v[70:73], v[26:29], v[6:9], v[70:73]
	v_subrev_u32_e32 v26, s20, v181
	v_mfma_f32_16x16x32_bf16 v[66:69], v[14:17], v[22:25], v[66:69]
	v_mfma_f32_16x16x32_bf16 v[62:65], v[14:17], v[18:21], v[62:65]
	v_mfma_f32_16x16x32_bf16 v[58:61], v[14:17], v[10:13], v[58:61]
	v_mfma_f32_16x16x32_bf16 v[54:57], v[14:17], v[6:9], v[54:57]
	v_subrev_u32_e32 v14, s20, v203
	v_add_u32_e32 v16, v191, v26
	v_add_u32_e32 v14, v191, v14
	v_mfma_f32_16x16x32_bf16 v[38:41], v[30:33], v[22:25], v[38:41]
	v_subrev_u32_e32 v15, s23, v204
	v_mfma_f32_16x16x32_bf16 v[50:53], v[2:5], v[22:25], v[50:53]
	ds_read_b128 v[22:25], v16
	ds_read_b128 v[222:225], v16 offset:2048
	ds_read_b128 v[226:229], v16 offset:4096
	ds_read_b128 v[230:233], v16 offset:6144
	ds_read_b128 v[234:237], v14 offset:32768
	ds_read_b128 v[238:241], v14 offset:34816
	ds_read_b128 v[242:245], v14 offset:36864
	ds_read_b128 v[246:249], v14 offset:38912
	v_mfma_f32_16x16x32_bf16 v[90:93], v[30:33], v[18:21], v[90:93]
	v_mfma_f32_16x16x32_bf16 v[86:89], v[30:33], v[10:13], v[86:89]
	v_mfma_f32_16x16x32_bf16 v[94:97], v[30:33], v[6:9], v[94:97]
	v_mfma_f32_16x16x32_bf16 v[46:49], v[2:5], v[18:21], v[46:49]
	v_mfma_f32_16x16x32_bf16 v[42:45], v[2:5], v[10:13], v[42:45]
	v_mfma_f32_16x16x32_bf16 v[34:37], v[2:5], v[6:9], v[34:37]
	s_add_i32 s20, s6, 4
	s_mul_i32 s23, s20, 0xab
	s_bfe_u32 s23, s23, 0x70009
	s_mul_i32 s23, s23, 3
	s_sub_i32 s20, s20, s23
	s_and_b32 s20, s20, 0xff
	s_mul_i32 s20, s20, 0xc000
	s_waitcnt vmcnt(6)
	v_add_u32_e32 v2, v191, v15
	v_add_u32_e32 v6, v191, v252
	s_waitcnt lgkmcnt(0)
	v_mfma_f32_16x16x32_bf16 v[82:85], v[222:225], v[234:237], v[82:85]
	s_add_i32 s23, s20, s11
	s_waitcnt lgkmcnt(0)
	s_barrier
	v_mfma_f32_16x16x32_bf16 v[78:81], v[222:225], v[238:241], v[78:81]
	ds_read_b128 v[30:33], v2
	ds_read_b128 v[26:29], v2 offset:2048
	ds_read_b128 v[14:17], v2 offset:4096
	ds_read_b128 v[2:5], v2 offset:6144
	v_add_u32_e32 v7, v191, v251
	v_mfma_f32_16x16x32_bf16 v[74:77], v[222:225], v[242:245], v[74:77]
	s_mov_b32 m0, s23
	s_mov_b64 s[34:35], 0x180
	s_add_i32 s20, s20, s12
	v_mfma_f32_16x16x32_bf16 v[70:73], v[222:225], v[246:249], v[70:73]
	v_lshl_add_u64 v[222:223], v[118:119], 0, v[102:103]
	v_lshl_add_u64 v[224:225], v[222:223], 0, s[84:85]
	s_add_i32 s19, s19, 1
	v_mfma_f32_16x16x32_bf16 v[38:41], v[22:25], v[234:237], v[38:41]
	v_mfma_f32_16x16x32_bf16 v[90:93], v[22:25], v[238:241], v[90:93]
	v_mfma_f32_16x16x32_bf16 v[86:89], v[22:25], v[242:245], v[86:89]
	v_mfma_f32_16x16x32_bf16 v[94:97], v[22:25], v[246:249], v[94:97]
	ds_read_b128 v[22:25], v6
	ds_read_b128 v[18:21], v7
	v_add_u32_e32 v6, v191, v250
	ds_read_b128 v[10:13], v6
	ds_read_b128 v[6:9], v6 offset:2048
	global_load_lds_dwordx4 v[224:225], off
	v_lshl_add_u64 v[224:225], v[222:223], 0, s[76:77]
	s_add_i32 m0, s23, 0x400
	v_mfma_f32_16x16x32_bf16 v[66:69], v[226:229], v[234:237], v[66:69]
	global_load_lds_dwordx4 v[224:225], off
	v_lshl_add_u64 v[224:225], v[222:223], 0, s[54:55]
	s_add_i32 m0, s23, 0x800
	v_lshl_add_u64 v[222:223], v[222:223], 0, s[68:69]
	global_load_lds_dwordx4 v[224:225], off
	s_add_i32 m0, s23, 0xc00
	v_mfma_f32_16x16x32_bf16 v[62:65], v[226:229], v[238:241], v[62:65]
	global_load_lds_dwordx4 v[222:223], off
	v_lshl_add_u64 v[222:223], v[120:121], 0, v[102:103]
	v_lshl_add_u64 v[224:225], v[222:223], 0, s[34:35]
	s_add_i32 m0, s20, 0x8000
	s_mov_b64 s[34:35], 0x4180
	global_load_lds_dwordx4 v[224:225], off
	v_lshl_add_u64 v[222:223], v[222:223], 0, s[34:35]
	s_add_i32 m0, s20, 0x8400
	v_mfma_f32_16x16x32_bf16 v[58:61], v[226:229], v[242:245], v[58:61]
	global_load_lds_dwordx4 v[222:223], off
	v_mfma_f32_16x16x32_bf16 v[54:57], v[226:229], v[246:249], v[54:57]
	v_mfma_f32_16x16x32_bf16 v[50:53], v[230:233], v[234:237], v[50:53]
	v_mfma_f32_16x16x32_bf16 v[46:49], v[230:233], v[238:241], v[46:49]
	v_mfma_f32_16x16x32_bf16 v[42:45], v[230:233], v[242:245], v[42:45]
	v_mfma_f32_16x16x32_bf16 v[34:37], v[230:233], v[246:249], v[34:37]
	s_add_i32 s6, s6, 1
	s_add_i32 s13, s13, 0xc000
	s_add_i32 s14, s14, 1
	v_lshl_add_u64 v[118:119], v[118:119], 0, s[2:3]
	s_cmp_eq_u32 s13, 0x9c000
	v_lshl_add_u64 v[120:121], v[120:121], 0, s[2:3]
	s_cbranch_scc0 .LBB0_347
	s_waitcnt lgkmcnt(0)
	v_mfma_f32_16x16x32_bf16 v[38:41], v[30:33], v[22:25], v[38:41]
	v_mfma_f32_16x16x32_bf16 v[90:93], v[30:33], v[18:21], v[90:93]
	v_mfma_f32_16x16x32_bf16 v[86:89], v[30:33], v[10:13], v[86:89]
	v_mfma_f32_16x16x32_bf16 v[30:33], v[30:33], v[6:9], v[94:97]
	v_mfma_f32_16x16x32_bf16 v[82:85], v[26:29], v[22:25], v[82:85]
	v_mfma_f32_16x16x32_bf16 v[78:81], v[26:29], v[18:21], v[78:81]
	v_mfma_f32_16x16x32_bf16 v[74:77], v[26:29], v[10:13], v[74:77]
	v_mfma_f32_16x16x32_bf16 v[26:29], v[26:29], v[6:9], v[70:73]
	v_mfma_f32_16x16x32_bf16 v[66:69], v[14:17], v[22:25], v[66:69]
	v_mfma_f32_16x16x32_bf16 v[62:65], v[14:17], v[18:21], v[62:65]
	v_mfma_f32_16x16x32_bf16 v[58:61], v[14:17], v[10:13], v[58:61]
	v_mfma_f32_16x16x32_bf16 v[14:17], v[14:17], v[6:9], v[54:57]
	v_mfma_f32_16x16x32_bf16 v[22:25], v[2:5], v[22:25], v[50:53]
	v_mfma_f32_16x16x32_bf16 v[18:21], v[2:5], v[18:21], v[46:49]
	s_nop 2
	ds_read_b128 v[46:49], v205
	ds_read_b128 v[50:53], v206 offset:2048
	ds_read_b128 v[54:57], v206 offset:4096
	ds_read_b128 v[70:73], v206 offset:6144
	v_mfma_f32_16x16x32_bf16 v[10:13], v[2:5], v[10:13], v[42:45]
	s_nop 2
	ds_read_b128 v[42:45], v207 offset:32768
	ds_read_b128 v[94:97], v208 offset:34816
	ds_read_b128 v[118:121], v208 offset:36864
	ds_read_b128 v[222:225], v208 offset:38912
	v_mfma_f32_16x16x32_bf16 v[2:5], v[2:5], v[6:9], v[34:37]
	s_waitcnt lgkmcnt(0)
	v_mfma_f32_16x16x32_bf16 v[6:9], v[46:49], v[42:45], v[38:41]
	s_waitcnt vmcnt(6)
	s_waitcnt lgkmcnt(0)
	s_barrier
	v_mfma_f32_16x16x32_bf16 v[34:37], v[46:49], v[94:97], v[90:93]
	v_mfma_f32_16x16x32_bf16 v[38:41], v[46:49], v[118:121], v[86:89]
	s_nop 1
	v_add_u32_e32 v90, 0x20800, v212
	v_mfma_f32_16x16x32_bf16 v[30:33], v[46:49], v[222:225], v[30:33]
	v_mfma_f32_16x16x32_bf16 v[46:49], v[50:53], v[42:45], v[82:85]
	v_mfma_f32_16x16x32_bf16 v[78:81], v[50:53], v[94:97], v[78:81]
	v_mfma_f32_16x16x32_bf16 v[74:77], v[50:53], v[118:121], v[74:77]
	v_mfma_f32_16x16x32_bf16 v[26:29], v[50:53], v[222:225], v[26:29]
	v_mfma_f32_16x16x32_bf16 v[50:53], v[54:57], v[42:45], v[66:69]
	v_mfma_f32_16x16x32_bf16 v[62:65], v[54:57], v[94:97], v[62:65]
	v_mfma_f32_16x16x32_bf16 v[58:61], v[54:57], v[118:121], v[58:61]
	v_mfma_f32_16x16x32_bf16 v[14:17], v[54:57], v[222:225], v[14:17]
	v_add_u32_e32 v54, v180, v124
	ds_read_b128 v[54:57], v54
	ds_read_b128 v[66:69], v209 offset:2048
	v_mfma_f32_16x16x32_bf16 v[18:21], v[70:73], v[94:97], v[18:21]
	v_add_u32_e32 v94, 0x21000, v212
	v_mfma_f32_16x16x32_bf16 v[10:13], v[70:73], v[118:121], v[10:13]
	v_add_u32_e32 v118, 0x21800, v212
	v_mfma_f32_16x16x32_bf16 v[22:25], v[70:73], v[42:45], v[22:25]
	ds_read_b128 v[42:45], v209 offset:4096
	ds_read_b128 v[82:85], v209 offset:6144
	ds_read_b128 v[86:89], v211
	ds_read_b128 v[90:93], v90
	ds_read_b128 v[94:97], v94
	ds_read_b128 v[118:121], v118
	v_mfma_f32_16x16x32_bf16 v[2:5], v[70:73], v[222:225], v[2:5]
	s_waitcnt lgkmcnt(0)
	v_mfma_f32_16x16x32_bf16 v[50:53], v[42:45], v[86:89], v[50:53]
	v_mfma_f32_16x16x32_bf16 v[62:65], v[42:45], v[90:93], v[62:65]
	v_mfma_f32_16x16x32_bf16 v[58:61], v[42:45], v[94:97], v[58:61]
	v_mfma_f32_16x16x32_bf16 v[14:17], v[42:45], v[118:121], v[14:17]
	v_add_u32_e32 v42, v180, v128
	v_mfma_f32_16x16x32_bf16 v[6:9], v[54:57], v[86:89], v[6:9]
	v_mfma_f32_16x16x32_bf16 v[34:37], v[54:57], v[90:93], v[34:37]
	v_mfma_f32_16x16x32_bf16 v[38:41], v[54:57], v[94:97], v[38:41]
	v_mfma_f32_16x16x32_bf16 v[30:33], v[54:57], v[118:121], v[30:33]
	v_mfma_f32_16x16x32_bf16 v[46:49], v[66:69], v[86:89], v[46:49]
	v_mfma_f32_16x16x32_bf16 v[54:57], v[66:69], v[90:93], v[78:81]
	v_mfma_f32_16x16x32_bf16 v[70:73], v[66:69], v[94:97], v[74:77]
	v_mfma_f32_16x16x32_bf16 v[26:29], v[66:69], v[118:121], v[26:29]
	ds_read_b128 v[42:45], v42
	ds_read_b128 v[66:69], v213
	ds_read_b128 v[74:77], v214
	ds_read_b128 v[78:81], v215
	v_mfma_f32_16x16x32_bf16 v[22:25], v[82:85], v[86:89], v[22:25]
	v_mfma_f32_16x16x32_bf16 v[18:21], v[82:85], v[90:93], v[18:21]
	v_mfma_f32_16x16x32_bf16 v[10:13], v[82:85], v[94:97], v[10:13]
	ds_read_b128 v[86:89], v216
	ds_read_b128 v[90:93], v217
	ds_read_b128 v[94:97], v218
	ds_read_b128 v[222:225], v219
	v_mfma_f32_16x16x32_bf16 v[2:5], v[82:85], v[118:121], v[2:5]
	s_waitcnt vmcnt(0)
	s_waitcnt lgkmcnt(0)
	v_mfma_f32_16x16x32_bf16 v[6:9], v[42:45], v[86:89], v[6:9]
	s_waitcnt lgkmcnt(0)
	s_barrier
	v_mfma_f32_16x16x32_bf16 v[34:37], v[42:45], v[90:93], v[34:37]
	v_mfma_f32_16x16x32_bf16 v[38:41], v[42:45], v[94:97], v[38:41]
	v_mfma_f32_16x16x32_bf16 v[30:33], v[42:45], v[222:225], v[30:33]
	v_mfma_f32_16x16x32_bf16 v[42:45], v[66:69], v[86:89], v[46:49]
	v_mfma_f32_16x16x32_bf16 v[46:49], v[66:69], v[90:93], v[54:57]
	v_mfma_f32_16x16x32_bf16 v[54:57], v[66:69], v[94:97], v[70:73]
	v_mfma_f32_16x16x32_bf16 v[26:29], v[66:69], v[222:225], v[26:29]
	v_mfma_f32_16x16x32_bf16 v[50:53], v[74:77], v[86:89], v[50:53]
	v_mfma_f32_16x16x32_bf16 v[62:65], v[74:77], v[90:93], v[62:65]
	v_mfma_f32_16x16x32_bf16 v[58:61], v[74:77], v[94:97], v[58:61]
	v_mfma_f32_16x16x32_bf16 v[14:17], v[74:77], v[222:225], v[14:17]
	ds_read_b128 v[66:69], v212 offset:38912
	ds_read_b128 v[70:73], v212 offset:36864
	ds_read_b128 v[74:77], v212 offset:34816
	ds_read_b128 v[82:85], v210 offset:32768
	v_mfma_f32_16x16x32_bf16 v[22:25], v[78:81], v[86:89], v[22:25]
	v_mfma_f32_16x16x32_bf16 v[18:21], v[78:81], v[90:93], v[18:21]
	v_mfma_f32_16x16x32_bf16 v[10:13], v[78:81], v[94:97], v[10:13]
	ds_read_b128 v[86:89], v221 offset:6144
	ds_read_b128 v[90:93], v221 offset:4096
	ds_read_b128 v[94:97], v221 offset:2048
	ds_read_b128 v[118:121], v117
	v_mfma_f32_16x16x32_bf16 v[2:5], v[78:81], v[222:225], v[2:5]
	s_waitcnt lgkmcnt(0)
	v_mfma_f32_16x16x32_bf16 v[42:45], v[94:97], v[82:85], v[42:45]
	v_add_u32_e32 v78, v123, v128
	v_add_u32_e32 v117, v127, v128
	v_mfma_f32_16x16x32_bf16 v[46:49], v[94:97], v[74:77], v[46:49]
	v_mfma_f32_16x16x32_bf16 v[54:57], v[94:97], v[70:73], v[54:57]
	v_mfma_f32_16x16x32_bf16 v[26:29], v[94:97], v[66:69], v[26:29]
	v_add_u32_e32 v94, v126, v128
	v_mfma_f32_16x16x32_bf16 v[50:53], v[90:93], v[82:85], v[50:53]
	v_mfma_f32_16x16x32_bf16 v[62:65], v[90:93], v[74:77], v[62:65]
	v_mfma_f32_16x16x32_bf16 v[58:61], v[90:93], v[70:73], v[58:61]
	v_mfma_f32_16x16x32_bf16 v[14:17], v[90:93], v[66:69], v[14:17]
	v_add_u32_e32 v90, v125, v128
	v_mfma_f32_16x16x32_bf16 v[6:9], v[118:121], v[82:85], v[6:9]
	v_mfma_f32_16x16x32_bf16 v[34:37], v[118:121], v[74:77], v[34:37]
	v_mfma_f32_16x16x32_bf16 v[38:41], v[118:121], v[70:73], v[38:41]
	v_mfma_f32_16x16x32_bf16 v[30:33], v[118:121], v[66:69], v[30:33]
	v_mfma_f32_16x16x32_bf16 v[22:25], v[86:89], v[82:85], v[22:25]
	ds_read_b128 v[78:81], v78
	ds_read_b128 v[82:85], v90 offset:2048
	v_mfma_f32_16x16x32_bf16 v[18:21], v[86:89], v[74:77], v[18:21]
	ds_read_b128 v[74:77], v90 offset:4096
	ds_read_b128 v[90:93], v90 offset:6144
	v_mfma_f32_16x16x32_bf16 v[10:13], v[86:89], v[70:73], v[10:13]
	ds_read_b128 v[70:73], v94 offset:32768
	ds_read_b128 v[94:97], v117 offset:34816
	ds_read_b128 v[118:121], v117 offset:36864
	ds_read_b128 v[222:225], v117 offset:38912
	v_mfma_f32_16x16x32_bf16 v[2:5], v[86:89], v[66:69], v[2:5]
	s_waitcnt vmcnt(0)
	s_waitcnt lgkmcnt(0)
	s_waitcnt lgkmcnt(0)
	v_mfma_f32_16x16x32_bf16 v[6:9], v[78:81], v[70:73], v[6:9]
	s_barrier
	v_mfma_f32_16x16x32_bf16 v[34:37], v[78:81], v[94:97], v[34:37]
	v_mfma_f32_16x16x32_bf16 v[38:41], v[78:81], v[118:121], v[38:41]
	v_mfma_f32_16x16x32_bf16 v[30:33], v[78:81], v[222:225], v[30:33]
	v_mfma_f32_16x16x32_bf16 v[42:45], v[82:85], v[70:73], v[42:45]
	v_mfma_f32_16x16x32_bf16 v[46:49], v[82:85], v[94:97], v[46:49]
	v_mfma_f32_16x16x32_bf16 v[54:57], v[82:85], v[118:121], v[54:57]
	v_mfma_f32_16x16x32_bf16 v[26:29], v[82:85], v[222:225], v[26:29]
	v_mfma_f32_16x16x32_bf16 v[50:53], v[74:77], v[70:73], v[50:53]
	v_mfma_f32_16x16x32_bf16 v[62:65], v[74:77], v[94:97], v[62:65]
	v_mfma_f32_16x16x32_bf16 v[58:61], v[74:77], v[118:121], v[58:61]
	v_mfma_f32_16x16x32_bf16 v[14:17], v[74:77], v[222:225], v[14:17]
	v_mfma_f32_16x16x32_bf16 v[22:25], v[90:93], v[70:73], v[22:25]
	v_mfma_f32_16x16x32_bf16 v[18:21], v[90:93], v[94:97], v[18:21]
	v_mfma_f32_16x16x32_bf16 v[10:13], v[90:93], v[118:121], v[10:13]
	v_mfma_f32_16x16x32_bf16 v[2:5], v[90:93], v[222:225], v[2:5]
	s_waitcnt lgkmcnt(0)
	s_barrier
	v_mov_b32_e32 v230, s75
	v_mov_b32_e32 v231, 0xaaaaaaab
	v_mul_hi_u32 v231, v230, v231
	v_lshrrev_b32_e32 v231, 4, v231
	v_cmp_gt_u32_e32 vcc, 26, v231
	s_nop 4
	s_cmp_lg_u64 vcc, 0
	s_cbranch_scc0 .Lipe_fallback
	s_mul_hi_i32 s6, s75, 0x2aaaaaab
	s_lshr_b32 s13, s6, 31
	s_ashr_i32 s6, s6, 2
	s_add_i32 s6, s6, s13
	s_mul_i32 s13, s6, 24
	s_sub_i32 s13, s75, s13
	v_readfirstlane_b32 s14, v137
	s_lshr_b32 s14, s14, 6
	s_and_b32 s19, s14, 1
	s_lshr_b32 s20, s14, 1
	s_lshl_b32 s13, s13, 8
	s_lshl_b32 s20, s20, 6
	s_add_i32 s13, s13, s20
	s_lshl_b32 s6, s6, 7
	s_lshl_b32 s19, s19, 6
	s_add_i32 s6, s6, s19
	s_mul_i32 s14, s14, 0x4100
	s_lshr_b32 s20, s6, 8
	s_cmpk_lt_i32 s13, 0x1000
	s_cselect_b32 s19, 1, 0
	s_and_b32 s46, s13, 0xff
	s_add_i32 s47, s13, 0xfffff000
	s_and_b32 s47, s47, 0x3ff
	s_cmp_lg_u32 s19, 0
	s_cselect_b32 s46, s46, s47
	s_sub_i32 s47, s13, s46
	v_and_b32_e32 v221, 63, v137
	v_and_b32_e32 v222, 15, v221
	v_lshrrev_b32_e32 v223, 4, v221
	v_and_b32_e32 v224, 3, v222
	v_lshrrev_b32_e32 v225, 2, v222
	v_lshl_or_b32 v226, v223, 2, v224
	v_lshl_add_u32 v232, v221, 4, s14
	v_lshrrev_b32_e32 v236, 3, v221
	v_and_b32_e32 v237, 7, v221
	v_xor_b32_e32 v237, v237, v236
	s_mov_b32 s16, 0xd30
	s_lshr_b32 s16, s16, s20
	s_and_b32 s16, s16, 1
	s_cbranch_scc0 .Lipe_noT
	s_mov_b32 s22, 0xae78000
	s_mov_b32 s23, 9
	s_sub_i32 s26, s6, 1024
	s_add_i32 s27, s6, 0xfffff800
	s_cmp_eq_u32 s20, 8
	s_cselect_b32 s22, 0xb478000, s22
	s_cselect_b32 s23, 8, s23
	s_cselect_b32 s26, s27, s26
	s_add_i32 s27, s6, 0xfffff600
	s_cmp_eq_u32 s20, 10
	s_cselect_b32 s22, 0xba78000, s22
	s_cselect_b32 s23, 8, s23
	s_cselect_b32 s26, s27, s26
	s_add_i32 s27, s6, 0xfffff500
	s_cmp_eq_u32 s20, 11
	s_cselect_b32 s22, 0xb778000, s22
	s_cselect_b32 s23, 8, s23
	s_cselect_b32 s26, s27, s26
	s_lshl_b32 s27, s47, 1
	s_lshl_b32 s27, s27, s23
	s_add_i32 s22, s22, s27
	s_lshr_b32 s27, s46, 5
	s_lshl_b32 s27, s27, 6
	s_lshl_b32 s27, s27, s23
	s_add_i32 s22, s22, s27
	s_lshl_b32 s27, s26, 6
	s_add_i32 s22, s22, s27
	v_lshrrev_b32_e32 v233, 2, v237
	v_lshlrev_b32_e32 v233, 6, v233
	v_lshlrev_b32_e32 v233, s23, v233
	v_lshl_add_u32 v233, v236, 6, v233
	v_and_b32_e32 v234, 3, v237
	v_lshl_add_u32 v233, v234, 4, v233
	v_add_u32_e32 v233, s22, v233
	v_and_b32_e32 v227, 7, v222
	v_lshlrev_b32_e32 v227, 1, v227
	v_or_b32_e32 v228, 0, v223
	v_xor_b32_e32 v228, v228, v227
	v_lshlrev_b32_e32 v228, 3, v228
	v_lshl_add_u32 v228, v222, 7, v228
	v_add_u32_e32 v228, s14, v228
	v_or_b32_e32 v229, 4, v223
	v_xor_b32_e32 v229, v229, v227
	v_lshlrev_b32_e32 v229, 3, v229
	v_lshl_add_u32 v229, v222, 7, v229
	v_add_u32_e32 v229, s14, v229
	v_or_b32_e32 v230, 8, v223
	v_xor_b32_e32 v230, v230, v227
	v_lshlrev_b32_e32 v230, 3, v230
	v_lshl_add_u32 v230, v222, 7, v230
	v_add_u32_e32 v230, s14, v230
	v_or_b32_e32 v231, 12, v223
	v_xor_b32_e32 v231, v231, v227
	v_lshlrev_b32_e32 v231, 3, v231
	v_lshl_add_u32 v231, v222, 7, v231
	v_add_u32_e32 v231, s14, v231
	v_cvt_pk_bf16_f32 v66, v6, v7
	v_cvt_pk_bf16_f32 v67, v8, v9
	ds_write_b64 v228, v[66:67] offset:0
	v_cvt_pk_bf16_f32 v70, v34, v35
	v_cvt_pk_bf16_f32 v71, v36, v37
	ds_write_b64 v228, v[70:71] offset:2048
	v_cvt_pk_bf16_f32 v74, v38, v39
	v_cvt_pk_bf16_f32 v75, v40, v41
	ds_write_b64 v228, v[74:75] offset:4096
	v_cvt_pk_bf16_f32 v78, v30, v31
	v_cvt_pk_bf16_f32 v79, v32, v33
	ds_write_b64 v228, v[78:79] offset:6144
	v_cvt_pk_bf16_f32 v82, v42, v43
	v_cvt_pk_bf16_f32 v83, v44, v45
	ds_write_b64 v229, v[82:83] offset:0
	v_cvt_pk_bf16_f32 v86, v46, v47
	v_cvt_pk_bf16_f32 v87, v48, v49
	ds_write_b64 v229, v[86:87] offset:2048
	v_cvt_pk_bf16_f32 v90, v54, v55
	v_cvt_pk_bf16_f32 v91, v56, v57
	ds_write_b64 v229, v[90:91] offset:4096
	v_cvt_pk_bf16_f32 v94, v26, v27
	v_cvt_pk_bf16_f32 v95, v28, v29
	ds_write_b64 v229, v[94:95] offset:6144
	v_cvt_pk_bf16_f32 v66, v50, v51
	v_cvt_pk_bf16_f32 v67, v52, v53
	ds_write_b64 v230, v[66:67] offset:0
	v_cvt_pk_bf16_f32 v70, v62, v63
	v_cvt_pk_bf16_f32 v71, v64, v65
	ds_write_b64 v230, v[70:71] offset:2048
	v_cvt_pk_bf16_f32 v74, v58, v59
	v_cvt_pk_bf16_f32 v75, v60, v61
	ds_write_b64 v230, v[74:75] offset:4096
	v_cvt_pk_bf16_f32 v78, v14, v15
	v_cvt_pk_bf16_f32 v79, v16, v17
	ds_write_b64 v230, v[78:79] offset:6144
	v_cvt_pk_bf16_f32 v82, v22, v23
	v_cvt_pk_bf16_f32 v83, v24, v25
	ds_write_b64 v231, v[82:83] offset:0
	v_cvt_pk_bf16_f32 v86, v18, v19
	v_cvt_pk_bf16_f32 v87, v20, v21
	ds_write_b64 v231, v[86:87] offset:2048
	v_cvt_pk_bf16_f32 v90, v10, v11
	v_cvt_pk_bf16_f32 v91, v12, v13
	ds_write_b64 v231, v[90:91] offset:4096
	v_cvt_pk_bf16_f32 v94, v2, v3
	v_cvt_pk_bf16_f32 v95, v4, v5
	ds_write_b64 v231, v[94:95] offset:6144
	s_waitcnt lgkmcnt(0)
	ds_read_b128 v[66:69], v232 offset:0
	ds_read_b128 v[70:73], v232 offset:1024
	ds_read_b128 v[74:77], v232 offset:2048
	ds_read_b128 v[78:81], v232 offset:3072
	ds_read_b128 v[82:85], v232 offset:4096
	ds_read_b128 v[86:89], v232 offset:5120
	ds_read_b128 v[90:93], v232 offset:6144
	ds_read_b128 v[94:97], v232 offset:7168
	s_waitcnt lgkmcnt(7)
	global_store_dwordx4 v233, v[66:69], s[94:95] sc1
	s_waitcnt lgkmcnt(6)
	v_add_u32_e32 v235, 0x200, v233
	global_store_dwordx4 v235, v[70:73], s[94:95] sc1
	s_waitcnt lgkmcnt(5)
	v_add_u32_e32 v235, 0x400, v233
	global_store_dwordx4 v235, v[74:77], s[94:95] sc1
	s_waitcnt lgkmcnt(4)
	v_add_u32_e32 v235, 0x600, v233
	global_store_dwordx4 v235, v[78:81], s[94:95] sc1
	s_waitcnt lgkmcnt(3)
	v_add_u32_e32 v235, 0x800, v233
	global_store_dwordx4 v235, v[82:85], s[94:95] sc1
	s_waitcnt lgkmcnt(2)
	v_add_u32_e32 v235, 0xa00, v233
	global_store_dwordx4 v235, v[86:89], s[94:95] sc1
	s_waitcnt lgkmcnt(1)
	v_add_u32_e32 v235, 0xc00, v233
	global_store_dwordx4 v235, v[90:93], s[94:95] sc1
	s_waitcnt lgkmcnt(0)
	v_add_u32_e32 v235, 0xe00, v233
	global_store_dwordx4 v235, v[94:97], s[94:95] sc1
	s_nop 1
.Lipe_noT:
	s_mov_b32 s16, 0x16cf
	s_lshr_b32 s16, s16, s20
	s_and_b32 s16, s16, 1
	s_mov_b32 s17, 0x1bc
	s_lshr_b32 s17, s17, s20
	s_and_b32 s17, s17, s19
	s_or_b32 s22, s16, s17
	s_cmp_lg_u32 s22, 0
	s_cbranch_scc0 .LBB0_345
	s_mov_b32 s34, 0xaaaaaaaa
	s_mov_b32 s35, 0xaaaaaaaa
	s_mov_b32 s36, 0xcccccccc
	s_mov_b32 s37, 0xcccccccc
	s_nop 1
	v_mov_b32_dpp v66, v7 quad_perm:[1,0,3,2] row_mask:0xf bank_mask:0xf
	v_mov_b32_dpp v67, v6 quad_perm:[1,0,3,2] row_mask:0xf bank_mask:0xf
	v_mov_b32_dpp v68, v9 quad_perm:[1,0,3,2] row_mask:0xf bank_mask:0xf
	v_mov_b32_dpp v69, v8 quad_perm:[1,0,3,2] row_mask:0xf bank_mask:0xf
	v_cndmask_b32_e64 v6, v6, v66, s[34:35]
	v_cndmask_b32_e64 v7, v67, v7, s[34:35]
	v_cndmask_b32_e64 v8, v8, v68, s[34:35]
	v_cndmask_b32_e64 v9, v69, v9, s[34:35]
	s_nop 1
	v_mov_b32_dpp v68, v6 quad_perm:[2,3,0,1] row_mask:0xf bank_mask:0xf
	v_mov_b32_dpp v69, v7 quad_perm:[2,3,0,1] row_mask:0xf bank_mask:0xf
	v_mov_b32_dpp v66, v8 quad_perm:[2,3,0,1] row_mask:0xf bank_mask:0xf
	v_mov_b32_dpp v67, v9 quad_perm:[2,3,0,1] row_mask:0xf bank_mask:0xf
	v_cndmask_b32_e64 v6, v6, v66, s[36:37]
	v_cndmask_b32_e64 v7, v7, v67, s[36:37]
	v_cndmask_b32_e64 v8, v68, v8, s[36:37]
	v_cndmask_b32_e64 v9, v69, v9, s[36:37]
	s_nop 1
	v_mov_b32_dpp v66, v35 quad_perm:[1,0,3,2] row_mask:0xf bank_mask:0xf
	v_mov_b32_dpp v67, v34 quad_perm:[1,0,3,2] row_mask:0xf bank_mask:0xf
	v_mov_b32_dpp v68, v37 quad_perm:[1,0,3,2] row_mask:0xf bank_mask:0xf
	v_mov_b32_dpp v69, v36 quad_perm:[1,0,3,2] row_mask:0xf bank_mask:0xf
	v_cndmask_b32_e64 v34, v34, v66, s[34:35]
	v_cndmask_b32_e64 v35, v67, v35, s[34:35]
	v_cndmask_b32_e64 v36, v36, v68, s[34:35]
	v_cndmask_b32_e64 v37, v69, v37, s[34:35]
	s_nop 1
	v_mov_b32_dpp v68, v34 quad_perm:[2,3,0,1] row_mask:0xf bank_mask:0xf
	v_mov_b32_dpp v69, v35 quad_perm:[2,3,0,1] row_mask:0xf bank_mask:0xf
	v_mov_b32_dpp v66, v36 quad_perm:[2,3,0,1] row_mask:0xf bank_mask:0xf
	v_mov_b32_dpp v67, v37 quad_perm:[2,3,0,1] row_mask:0xf bank_mask:0xf
	v_cndmask_b32_e64 v34, v34, v66, s[36:37]
	v_cndmask_b32_e64 v35, v35, v67, s[36:37]
	v_cndmask_b32_e64 v36, v68, v36, s[36:37]
	v_cndmask_b32_e64 v37, v69, v37, s[36:37]
	s_nop 1
	v_mov_b32_dpp v66, v39 quad_perm:[1,0,3,2] row_mask:0xf bank_mask:0xf
	v_mov_b32_dpp v67, v38 quad_perm:[1,0,3,2] row_mask:0xf bank_mask:0xf
	v_mov_b32_dpp v68, v41 quad_perm:[1,0,3,2] row_mask:0xf bank_mask:0xf
	v_mov_b32_dpp v69, v40 quad_perm:[1,0,3,2] row_mask:0xf bank_mask:0xf
	v_cndmask_b32_e64 v38, v38, v66, s[34:35]
	v_cndmask_b32_e64 v39, v67, v39, s[34:35]
	v_cndmask_b32_e64 v40, v40, v68, s[34:35]
	v_cndmask_b32_e64 v41, v69, v41, s[34:35]
	s_nop 1
	v_mov_b32_dpp v68, v38 quad_perm:[2,3,0,1] row_mask:0xf bank_mask:0xf
	v_mov_b32_dpp v69, v39 quad_perm:[2,3,0,1] row_mask:0xf bank_mask:0xf
	v_mov_b32_dpp v66, v40 quad_perm:[2,3,0,1] row_mask:0xf bank_mask:0xf
	v_mov_b32_dpp v67, v41 quad_perm:[2,3,0,1] row_mask:0xf bank_mask:0xf
	v_cndmask_b32_e64 v38, v38, v66, s[36:37]
	v_cndmask_b32_e64 v39, v39, v67, s[36:37]
	v_cndmask_b32_e64 v40, v68, v40, s[36:37]
	v_cndmask_b32_e64 v41, v69, v41, s[36:37]
	s_nop 1
	v_mov_b32_dpp v66, v31 quad_perm:[1,0,3,2] row_mask:0xf bank_mask:0xf
	v_mov_b32_dpp v67, v30 quad_perm:[1,0,3,2] row_mask:0xf bank_mask:0xf
	v_mov_b32_dpp v68, v33 quad_perm:[1,0,3,2] row_mask:0xf bank_mask:0xf
	v_mov_b32_dpp v69, v32 quad_perm:[1,0,3,2] row_mask:0xf bank_mask:0xf
	v_cndmask_b32_e64 v30, v30, v66, s[34:35]
	v_cndmask_b32_e64 v31, v67, v31, s[34:35]
	v_cndmask_b32_e64 v32, v32, v68, s[34:35]
	v_cndmask_b32_e64 v33, v69, v33, s[34:35]
	s_nop 1
	v_mov_b32_dpp v68, v30 quad_perm:[2,3,0,1] row_mask:0xf bank_mask:0xf
	v_mov_b32_dpp v69, v31 quad_perm:[2,3,0,1] row_mask:0xf bank_mask:0xf
	v_mov_b32_dpp v66, v32 quad_perm:[2,3,0,1] row_mask:0xf bank_mask:0xf
	v_mov_b32_dpp v67, v33 quad_perm:[2,3,0,1] row_mask:0xf bank_mask:0xf
	v_cndmask_b32_e64 v30, v30, v66, s[36:37]
	v_cndmask_b32_e64 v31, v31, v67, s[36:37]
	v_cndmask_b32_e64 v32, v68, v32, s[36:37]
	v_cndmask_b32_e64 v33, v69, v33, s[36:37]
	s_nop 1
	v_mov_b32_dpp v66, v43 quad_perm:[1,0,3,2] row_mask:0xf bank_mask:0xf
	v_mov_b32_dpp v67, v42 quad_perm:[1,0,3,2] row_mask:0xf bank_mask:0xf
	v_mov_b32_dpp v68, v45 quad_perm:[1,0,3,2] row_mask:0xf bank_mask:0xf
	v_mov_b32_dpp v69, v44 quad_perm:[1,0,3,2] row_mask:0xf bank_mask:0xf
	v_cndmask_b32_e64 v42, v42, v66, s[34:35]
	v_cndmask_b32_e64 v43, v67, v43, s[34:35]
	v_cndmask_b32_e64 v44, v44, v68, s[34:35]
	v_cndmask_b32_e64 v45, v69, v45, s[34:35]
	s_nop 1
	v_mov_b32_dpp v68, v42 quad_perm:[2,3,0,1] row_mask:0xf bank_mask:0xf
	v_mov_b32_dpp v69, v43 quad_perm:[2,3,0,1] row_mask:0xf bank_mask:0xf
	v_mov_b32_dpp v66, v44 quad_perm:[2,3,0,1] row_mask:0xf bank_mask:0xf
	v_mov_b32_dpp v67, v45 quad_perm:[2,3,0,1] row_mask:0xf bank_mask:0xf
	v_cndmask_b32_e64 v42, v42, v66, s[36:37]
	v_cndmask_b32_e64 v43, v43, v67, s[36:37]
	v_cndmask_b32_e64 v44, v68, v44, s[36:37]
	v_cndmask_b32_e64 v45, v69, v45, s[36:37]
	s_nop 1
	v_mov_b32_dpp v66, v47 quad_perm:[1,0,3,2] row_mask:0xf bank_mask:0xf
	v_mov_b32_dpp v67, v46 quad_perm:[1,0,3,2] row_mask:0xf bank_mask:0xf
	v_mov_b32_dpp v68, v49 quad_perm:[1,0,3,2] row_mask:0xf bank_mask:0xf
	v_mov_b32_dpp v69, v48 quad_perm:[1,0,3,2] row_mask:0xf bank_mask:0xf
	v_cndmask_b32_e64 v46, v46, v66, s[34:35]
	v_cndmask_b32_e64 v47, v67, v47, s[34:35]
	v_cndmask_b32_e64 v48, v48, v68, s[34:35]
	v_cndmask_b32_e64 v49, v69, v49, s[34:35]
	s_nop 1
	v_mov_b32_dpp v68, v46 quad_perm:[2,3,0,1] row_mask:0xf bank_mask:0xf
	v_mov_b32_dpp v69, v47 quad_perm:[2,3,0,1] row_mask:0xf bank_mask:0xf
	v_mov_b32_dpp v66, v48 quad_perm:[2,3,0,1] row_mask:0xf bank_mask:0xf
	v_mov_b32_dpp v67, v49 quad_perm:[2,3,0,1] row_mask:0xf bank_mask:0xf
	v_cndmask_b32_e64 v46, v46, v66, s[36:37]
	v_cndmask_b32_e64 v47, v47, v67, s[36:37]
	v_cndmask_b32_e64 v48, v68, v48, s[36:37]
	v_cndmask_b32_e64 v49, v69, v49, s[36:37]
	s_nop 1
	v_mov_b32_dpp v66, v55 quad_perm:[1,0,3,2] row_mask:0xf bank_mask:0xf
	v_mov_b32_dpp v67, v54 quad_perm:[1,0,3,2] row_mask:0xf bank_mask:0xf
	v_mov_b32_dpp v68, v57 quad_perm:[1,0,3,2] row_mask:0xf bank_mask:0xf
	v_mov_b32_dpp v69, v56 quad_perm:[1,0,3,2] row_mask:0xf bank_mask:0xf
	v_cndmask_b32_e64 v54, v54, v66, s[34:35]
	v_cndmask_b32_e64 v55, v67, v55, s[34:35]
	v_cndmask_b32_e64 v56, v56, v68, s[34:35]
	v_cndmask_b32_e64 v57, v69, v57, s[34:35]
	s_nop 1
	v_mov_b32_dpp v68, v54 quad_perm:[2,3,0,1] row_mask:0xf bank_mask:0xf
	v_mov_b32_dpp v69, v55 quad_perm:[2,3,0,1] row_mask:0xf bank_mask:0xf
	v_mov_b32_dpp v66, v56 quad_perm:[2,3,0,1] row_mask:0xf bank_mask:0xf
	v_mov_b32_dpp v67, v57 quad_perm:[2,3,0,1] row_mask:0xf bank_mask:0xf
	v_cndmask_b32_e64 v54, v54, v66, s[36:37]
	v_cndmask_b32_e64 v55, v55, v67, s[36:37]
	v_cndmask_b32_e64 v56, v68, v56, s[36:37]
	v_cndmask_b32_e64 v57, v69, v57, s[36:37]
	s_nop 1
	v_mov_b32_dpp v66, v27 quad_perm:[1,0,3,2] row_mask:0xf bank_mask:0xf
	v_mov_b32_dpp v67, v26 quad_perm:[1,0,3,2] row_mask:0xf bank_mask:0xf
	v_mov_b32_dpp v68, v29 quad_perm:[1,0,3,2] row_mask:0xf bank_mask:0xf
	v_mov_b32_dpp v69, v28 quad_perm:[1,0,3,2] row_mask:0xf bank_mask:0xf
	v_cndmask_b32_e64 v26, v26, v66, s[34:35]
	v_cndmask_b32_e64 v27, v67, v27, s[34:35]
	v_cndmask_b32_e64 v28, v28, v68, s[34:35]
	v_cndmask_b32_e64 v29, v69, v29, s[34:35]
	s_nop 1
	v_mov_b32_dpp v68, v26 quad_perm:[2,3,0,1] row_mask:0xf bank_mask:0xf
	v_mov_b32_dpp v69, v27 quad_perm:[2,3,0,1] row_mask:0xf bank_mask:0xf
	v_mov_b32_dpp v66, v28 quad_perm:[2,3,0,1] row_mask:0xf bank_mask:0xf
	v_mov_b32_dpp v67, v29 quad_perm:[2,3,0,1] row_mask:0xf bank_mask:0xf
	v_cndmask_b32_e64 v26, v26, v66, s[36:37]
	v_cndmask_b32_e64 v27, v27, v67, s[36:37]
	v_cndmask_b32_e64 v28, v68, v28, s[36:37]
	v_cndmask_b32_e64 v29, v69, v29, s[36:37]
	s_nop 1
	v_mov_b32_dpp v66, v51 quad_perm:[1,0,3,2] row_mask:0xf bank_mask:0xf
	v_mov_b32_dpp v67, v50 quad_perm:[1,0,3,2] row_mask:0xf bank_mask:0xf
	v_mov_b32_dpp v68, v53 quad_perm:[1,0,3,2] row_mask:0xf bank_mask:0xf
	v_mov_b32_dpp v69, v52 quad_perm:[1,0,3,2] row_mask:0xf bank_mask:0xf
	v_cndmask_b32_e64 v50, v50, v66, s[34:35]
	v_cndmask_b32_e64 v51, v67, v51, s[34:35]
	v_cndmask_b32_e64 v52, v52, v68, s[34:35]
	v_cndmask_b32_e64 v53, v69, v53, s[34:35]
	s_nop 1
	v_mov_b32_dpp v68, v50 quad_perm:[2,3,0,1] row_mask:0xf bank_mask:0xf
	v_mov_b32_dpp v69, v51 quad_perm:[2,3,0,1] row_mask:0xf bank_mask:0xf
	v_mov_b32_dpp v66, v52 quad_perm:[2,3,0,1] row_mask:0xf bank_mask:0xf
	v_mov_b32_dpp v67, v53 quad_perm:[2,3,0,1] row_mask:0xf bank_mask:0xf
	v_cndmask_b32_e64 v50, v50, v66, s[36:37]
	v_cndmask_b32_e64 v51, v51, v67, s[36:37]
	v_cndmask_b32_e64 v52, v68, v52, s[36:37]
	v_cndmask_b32_e64 v53, v69, v53, s[36:37]
	s_nop 1
	v_mov_b32_dpp v66, v63 quad_perm:[1,0,3,2] row_mask:0xf bank_mask:0xf
	v_mov_b32_dpp v67, v62 quad_perm:[1,0,3,2] row_mask:0xf bank_mask:0xf
	v_mov_b32_dpp v68, v65 quad_perm:[1,0,3,2] row_mask:0xf bank_mask:0xf
	v_mov_b32_dpp v69, v64 quad_perm:[1,0,3,2] row_mask:0xf bank_mask:0xf
	v_cndmask_b32_e64 v62, v62, v66, s[34:35]
	v_cndmask_b32_e64 v63, v67, v63, s[34:35]
	v_cndmask_b32_e64 v64, v64, v68, s[34:35]
	v_cndmask_b32_e64 v65, v69, v65, s[34:35]
	s_nop 1
	v_mov_b32_dpp v68, v62 quad_perm:[2,3,0,1] row_mask:0xf bank_mask:0xf
	v_mov_b32_dpp v69, v63 quad_perm:[2,3,0,1] row_mask:0xf bank_mask:0xf
	v_mov_b32_dpp v66, v64 quad_perm:[2,3,0,1] row_mask:0xf bank_mask:0xf
	v_mov_b32_dpp v67, v65 quad_perm:[2,3,0,1] row_mask:0xf bank_mask:0xf
	v_cndmask_b32_e64 v62, v62, v66, s[36:37]
	v_cndmask_b32_e64 v63, v63, v67, s[36:37]
	v_cndmask_b32_e64 v64, v68, v64, s[36:37]
	v_cndmask_b32_e64 v65, v69, v65, s[36:37]
	s_nop 1
	v_mov_b32_dpp v66, v59 quad_perm:[1,0,3,2] row_mask:0xf bank_mask:0xf
	v_mov_b32_dpp v67, v58 quad_perm:[1,0,3,2] row_mask:0xf bank_mask:0xf
	v_mov_b32_dpp v68, v61 quad_perm:[1,0,3,2] row_mask:0xf bank_mask:0xf
	v_mov_b32_dpp v69, v60 quad_perm:[1,0,3,2] row_mask:0xf bank_mask:0xf
	v_cndmask_b32_e64 v58, v58, v66, s[34:35]
	v_cndmask_b32_e64 v59, v67, v59, s[34:35]
	v_cndmask_b32_e64 v60, v60, v68, s[34:35]
	v_cndmask_b32_e64 v61, v69, v61, s[34:35]
	s_nop 1
	v_mov_b32_dpp v68, v58 quad_perm:[2,3,0,1] row_mask:0xf bank_mask:0xf
	v_mov_b32_dpp v69, v59 quad_perm:[2,3,0,1] row_mask:0xf bank_mask:0xf
	v_mov_b32_dpp v66, v60 quad_perm:[2,3,0,1] row_mask:0xf bank_mask:0xf
	v_mov_b32_dpp v67, v61 quad_perm:[2,3,0,1] row_mask:0xf bank_mask:0xf
	v_cndmask_b32_e64 v58, v58, v66, s[36:37]
	v_cndmask_b32_e64 v59, v59, v67, s[36:37]
	v_cndmask_b32_e64 v60, v68, v60, s[36:37]
	v_cndmask_b32_e64 v61, v69, v61, s[36:37]
	s_nop 1
	v_mov_b32_dpp v66, v15 quad_perm:[1,0,3,2] row_mask:0xf bank_mask:0xf
	v_mov_b32_dpp v67, v14 quad_perm:[1,0,3,2] row_mask:0xf bank_mask:0xf
	v_mov_b32_dpp v68, v17 quad_perm:[1,0,3,2] row_mask:0xf bank_mask:0xf
	v_mov_b32_dpp v69, v16 quad_perm:[1,0,3,2] row_mask:0xf bank_mask:0xf
	v_cndmask_b32_e64 v14, v14, v66, s[34:35]
	v_cndmask_b32_e64 v15, v67, v15, s[34:35]
	v_cndmask_b32_e64 v16, v16, v68, s[34:35]
	v_cndmask_b32_e64 v17, v69, v17, s[34:35]
	s_nop 1
	v_mov_b32_dpp v68, v14 quad_perm:[2,3,0,1] row_mask:0xf bank_mask:0xf
	v_mov_b32_dpp v69, v15 quad_perm:[2,3,0,1] row_mask:0xf bank_mask:0xf
	v_mov_b32_dpp v66, v16 quad_perm:[2,3,0,1] row_mask:0xf bank_mask:0xf
	v_mov_b32_dpp v67, v17 quad_perm:[2,3,0,1] row_mask:0xf bank_mask:0xf
	v_cndmask_b32_e64 v14, v14, v66, s[36:37]
	v_cndmask_b32_e64 v15, v15, v67, s[36:37]
	v_cndmask_b32_e64 v16, v68, v16, s[36:37]
	v_cndmask_b32_e64 v17, v69, v17, s[36:37]
	s_nop 1
	v_mov_b32_dpp v66, v23 quad_perm:[1,0,3,2] row_mask:0xf bank_mask:0xf
	v_mov_b32_dpp v67, v22 quad_perm:[1,0,3,2] row_mask:0xf bank_mask:0xf
	v_mov_b32_dpp v68, v25 quad_perm:[1,0,3,2] row_mask:0xf bank_mask:0xf
	v_mov_b32_dpp v69, v24 quad_perm:[1,0,3,2] row_mask:0xf bank_mask:0xf
	v_cndmask_b32_e64 v22, v22, v66, s[34:35]
	v_cndmask_b32_e64 v23, v67, v23, s[34:35]
	v_cndmask_b32_e64 v24, v24, v68, s[34:35]
	v_cndmask_b32_e64 v25, v69, v25, s[34:35]
	s_nop 1
	v_mov_b32_dpp v68, v22 quad_perm:[2,3,0,1] row_mask:0xf bank_mask:0xf
	v_mov_b32_dpp v69, v23 quad_perm:[2,3,0,1] row_mask:0xf bank_mask:0xf
	v_mov_b32_dpp v66, v24 quad_perm:[2,3,0,1] row_mask:0xf bank_mask:0xf
	v_mov_b32_dpp v67, v25 quad_perm:[2,3,0,1] row_mask:0xf bank_mask:0xf
	v_cndmask_b32_e64 v22, v22, v66, s[36:37]
	v_cndmask_b32_e64 v23, v23, v67, s[36:37]
	v_cndmask_b32_e64 v24, v68, v24, s[36:37]
	v_cndmask_b32_e64 v25, v69, v25, s[36:37]
	s_nop 1
	v_mov_b32_dpp v66, v19 quad_perm:[1,0,3,2] row_mask:0xf bank_mask:0xf
	v_mov_b32_dpp v67, v18 quad_perm:[1,0,3,2] row_mask:0xf bank_mask:0xf
	v_mov_b32_dpp v68, v21 quad_perm:[1,0,3,2] row_mask:0xf bank_mask:0xf
	v_mov_b32_dpp v69, v20 quad_perm:[1,0,3,2] row_mask:0xf bank_mask:0xf
	v_cndmask_b32_e64 v18, v18, v66, s[34:35]
	v_cndmask_b32_e64 v19, v67, v19, s[34:35]
	v_cndmask_b32_e64 v20, v20, v68, s[34:35]
	v_cndmask_b32_e64 v21, v69, v21, s[34:35]
	s_nop 1
	v_mov_b32_dpp v68, v18 quad_perm:[2,3,0,1] row_mask:0xf bank_mask:0xf
	v_mov_b32_dpp v69, v19 quad_perm:[2,3,0,1] row_mask:0xf bank_mask:0xf
	v_mov_b32_dpp v66, v20 quad_perm:[2,3,0,1] row_mask:0xf bank_mask:0xf
	v_mov_b32_dpp v67, v21 quad_perm:[2,3,0,1] row_mask:0xf bank_mask:0xf
	v_cndmask_b32_e64 v18, v18, v66, s[36:37]
	v_cndmask_b32_e64 v19, v19, v67, s[36:37]
	v_cndmask_b32_e64 v20, v68, v20, s[36:37]
	v_cndmask_b32_e64 v21, v69, v21, s[36:37]
	s_nop 1
	v_mov_b32_dpp v66, v11 quad_perm:[1,0,3,2] row_mask:0xf bank_mask:0xf
	v_mov_b32_dpp v67, v10 quad_perm:[1,0,3,2] row_mask:0xf bank_mask:0xf
	v_mov_b32_dpp v68, v13 quad_perm:[1,0,3,2] row_mask:0xf bank_mask:0xf
	v_mov_b32_dpp v69, v12 quad_perm:[1,0,3,2] row_mask:0xf bank_mask:0xf
	v_cndmask_b32_e64 v10, v10, v66, s[34:35]
	v_cndmask_b32_e64 v11, v67, v11, s[34:35]
	v_cndmask_b32_e64 v12, v12, v68, s[34:35]
	v_cndmask_b32_e64 v13, v69, v13, s[34:35]
	s_nop 1
	v_mov_b32_dpp v68, v10 quad_perm:[2,3,0,1] row_mask:0xf bank_mask:0xf
	v_mov_b32_dpp v69, v11 quad_perm:[2,3,0,1] row_mask:0xf bank_mask:0xf
	v_mov_b32_dpp v66, v12 quad_perm:[2,3,0,1] row_mask:0xf bank_mask:0xf
	v_mov_b32_dpp v67, v13 quad_perm:[2,3,0,1] row_mask:0xf bank_mask:0xf
	v_cndmask_b32_e64 v10, v10, v66, s[36:37]
	v_cndmask_b32_e64 v11, v11, v67, s[36:37]
	v_cndmask_b32_e64 v12, v68, v12, s[36:37]
	v_cndmask_b32_e64 v13, v69, v13, s[36:37]
	s_nop 1
	v_mov_b32_dpp v66, v3 quad_perm:[1,0,3,2] row_mask:0xf bank_mask:0xf
	v_mov_b32_dpp v67, v2 quad_perm:[1,0,3,2] row_mask:0xf bank_mask:0xf
	v_mov_b32_dpp v68, v5 quad_perm:[1,0,3,2] row_mask:0xf bank_mask:0xf
	v_mov_b32_dpp v69, v4 quad_perm:[1,0,3,2] row_mask:0xf bank_mask:0xf
	v_cndmask_b32_e64 v2, v2, v66, s[34:35]
	v_cndmask_b32_e64 v3, v67, v3, s[34:35]
	v_cndmask_b32_e64 v4, v4, v68, s[34:35]
	v_cndmask_b32_e64 v5, v69, v5, s[34:35]
	s_nop 1
	v_mov_b32_dpp v68, v2 quad_perm:[2,3,0,1] row_mask:0xf bank_mask:0xf
	v_mov_b32_dpp v69, v3 quad_perm:[2,3,0,1] row_mask:0xf bank_mask:0xf
	v_mov_b32_dpp v66, v4 quad_perm:[2,3,0,1] row_mask:0xf bank_mask:0xf
	v_mov_b32_dpp v67, v5 quad_perm:[2,3,0,1] row_mask:0xf bank_mask:0xf
	v_cndmask_b32_e64 v2, v2, v66, s[36:37]
	v_cndmask_b32_e64 v3, v3, v67, s[36:37]
	v_cndmask_b32_e64 v4, v68, v4, s[36:37]
	v_cndmask_b32_e64 v5, v69, v5, s[36:37]
	s_cmp_lg_u32 s17, 0
	s_cbranch_scc0 .Lipe_noO
	s_mov_b32 s22, 6291456
	s_mov_b32 s23, 7
	s_add_i32 s26, s6, 0xfffffe00
	s_add_i32 s27, s6, 0xfffffc00
	s_cmp_ge_u32 s20, 4
	s_cselect_b32 s22, 14680064, s22
	s_cselect_b32 s26, s27, s26
	s_add_i32 s27, s6, 0xfffff900
	s_cmp_eq_u32 s20, 7
	s_cselect_b32 s22, 23068672, s22
	s_cselect_b32 s23, 6, s23
	s_cselect_b32 s26, s27, s26
	s_add_i32 s27, s6, 0xfffff800
	s_cmp_eq_u32 s20, 8
	s_cselect_b32 s22, 27262976, s22
	s_cselect_b32 s23, 6, s23
	s_cselect_b32 s26, s27, s26
	v_readlane_b32 s27, v255, 40
	s_lshr_b32 s48, s47, 8
	s_lshl_b32 s48, s48, 4
	s_lshl_b32 s27, s27, 2
	s_add_i32 s48, s48, s27
	s_lshr_b32 s27, s26, s23
	s_add_i32 s48, s48, s27
	s_lshl_b32 s48, s48, 8
	s_add_i32 s48, s48, s46
	s_lshl_b32 s48, s48, s23
	s_lshl_b32 s27, s27, s23
	s_sub_i32 s27, s26, s27
	s_add_i32 s48, s48, s27
	s_add_i32 s48, s48, s22
	s_lshl_b32 s48, s48, 2
	v_lshlrev_b32_e32 v233, 1, v223
	v_xor_b32_e32 v233, v233, v222
	v_lshlrev_b32_e32 v233, 4, v233
	s_add_i32 s27, s23, 2
	v_lshlrev_b32_e32 v234, s27, v223
	v_add3_u32 v233, v233, v234, s48
	s_lshl_b32 s49, 16, s23
	v_and_b32_e32 v227, 3, v226
	v_lshlrev_b32_e32 v227, 1, v227
	v_or_b32_e32 v228, 0, v225
	v_xor_b32_e32 v228, v228, v227
	v_lshlrev_b32_e32 v228, 4, v228
	v_lshl_add_u32 v228, v226, 8, v228
	v_add_u32_e32 v228, s14, v228
	v_or_b32_e32 v229, 4, v225
	v_xor_b32_e32 v229, v229, v227
	v_lshlrev_b32_e32 v229, 4, v229
	v_lshl_add_u32 v229, v226, 8, v229
	v_add_u32_e32 v229, s14, v229
	v_or_b32_e32 v230, 8, v225
	v_xor_b32_e32 v230, v230, v227
	v_lshlrev_b32_e32 v230, 4, v230
	v_lshl_add_u32 v230, v226, 8, v230
	v_add_u32_e32 v230, s14, v230
	v_or_b32_e32 v231, 12, v225
	v_xor_b32_e32 v231, v231, v227
	v_lshlrev_b32_e32 v231, 4, v231
	v_lshl_add_u32 v231, v226, 8, v231
	v_add_u32_e32 v231, s14, v231
	ds_write_b128 v228, v[6:9] offset:0
	ds_write_b128 v229, v[34:37] offset:0
	ds_write_b128 v230, v[38:41] offset:0
	ds_write_b128 v231, v[30:33] offset:0
	ds_write_b128 v228, v[42:45] offset:4096
	ds_write_b128 v229, v[46:49] offset:4096
	ds_write_b128 v230, v[54:57] offset:4096
	ds_write_b128 v231, v[26:29] offset:4096
	ds_write_b128 v228, v[50:53] offset:8192
	ds_write_b128 v229, v[62:65] offset:8192
	ds_write_b128 v230, v[58:61] offset:8192
	ds_write_b128 v231, v[14:17] offset:8192
	ds_write_b128 v228, v[22:25] offset:12288
	ds_write_b128 v229, v[18:21] offset:12288
	ds_write_b128 v230, v[10:13] offset:12288
	ds_write_b128 v231, v[2:5] offset:12288
	s_waitcnt lgkmcnt(0)
	ds_read_b128 v[66:69], v232 offset:0
	ds_read_b128 v[70:73], v232 offset:1024
	ds_read_b128 v[74:77], v232 offset:2048
	ds_read_b128 v[78:81], v232 offset:3072
	ds_read_b128 v[82:85], v232 offset:4096
	ds_read_b128 v[86:89], v232 offset:5120
	ds_read_b128 v[90:93], v232 offset:6144
	ds_read_b128 v[94:97], v232 offset:7168
	s_waitcnt lgkmcnt(7)
	global_store_dwordx4 v233, v[66:69], s[92:93] sc1
	v_add_u32_e32 v233, s49, v233
	s_waitcnt lgkmcnt(6)
	global_store_dwordx4 v233, v[70:73], s[92:93] sc1
	v_add_u32_e32 v233, s49, v233
	s_waitcnt lgkmcnt(5)
	global_store_dwordx4 v233, v[74:77], s[92:93] sc1
	v_add_u32_e32 v233, s49, v233
	s_waitcnt lgkmcnt(4)
	global_store_dwordx4 v233, v[78:81], s[92:93] sc1
	v_add_u32_e32 v233, s49, v233
	s_waitcnt lgkmcnt(3)
	global_store_dwordx4 v233, v[82:85], s[92:93] sc1
	v_add_u32_e32 v233, s49, v233
	s_waitcnt lgkmcnt(2)
	global_store_dwordx4 v233, v[86:89], s[92:93] sc1
	v_add_u32_e32 v233, s49, v233
	s_waitcnt lgkmcnt(1)
	global_store_dwordx4 v233, v[90:93], s[92:93] sc1
	v_add_u32_e32 v233, s49, v233
	s_waitcnt lgkmcnt(0)
	global_store_dwordx4 v233, v[94:97], s[92:93] sc1
	v_add_u32_e32 v233, s49, v233
	s_nop 1
	ds_read_b128 v[66:69], v232 offset:8192
	ds_read_b128 v[70:73], v232 offset:9216
	ds_read_b128 v[74:77], v232 offset:10240
	ds_read_b128 v[78:81], v232 offset:11264
	ds_read_b128 v[82:85], v232 offset:12288
	ds_read_b128 v[86:89], v232 offset:13312
	ds_read_b128 v[90:93], v232 offset:14336
	ds_read_b128 v[94:97], v232 offset:15360
	s_waitcnt lgkmcnt(7)
	global_store_dwordx4 v233, v[66:69], s[92:93] sc1
	v_add_u32_e32 v233, s49, v233
	s_waitcnt lgkmcnt(6)
	global_store_dwordx4 v233, v[70:73], s[92:93] sc1
	v_add_u32_e32 v233, s49, v233
	s_waitcnt lgkmcnt(5)
	global_store_dwordx4 v233, v[74:77], s[92:93] sc1
	v_add_u32_e32 v233, s49, v233
	s_waitcnt lgkmcnt(4)
	global_store_dwordx4 v233, v[78:81], s[92:93] sc1
	v_add_u32_e32 v233, s49, v233
	s_waitcnt lgkmcnt(3)
	global_store_dwordx4 v233, v[82:85], s[92:93] sc1
	v_add_u32_e32 v233, s49, v233
	s_waitcnt lgkmcnt(2)
	global_store_dwordx4 v233, v[86:89], s[92:93] sc1
	v_add_u32_e32 v233, s49, v233
	s_waitcnt lgkmcnt(1)
	global_store_dwordx4 v233, v[90:93], s[92:93] sc1
	v_add_u32_e32 v233, s49, v233
	s_waitcnt lgkmcnt(0)
	global_store_dwordx4 v233, v[94:97], s[92:93] sc1
	v_add_u32_e32 v233, s49, v233
	s_nop 1

.Lipe_norope:
	v_and_b32_e32 v227, 7, v226
	v_lshlrev_b32_e32 v227, 1, v227
	v_or_b32_e32 v228, 0, v225
	v_xor_b32_e32 v228, v228, v227
	v_lshlrev_b32_e32 v228, 3, v228
	v_lshl_add_u32 v228, v226, 7, v228
	v_add_u32_e32 v228, s14, v228
	v_or_b32_e32 v229, 4, v225
	v_xor_b32_e32 v229, v229, v227
	v_lshlrev_b32_e32 v229, 3, v229
	v_lshl_add_u32 v229, v226, 7, v229
	v_add_u32_e32 v229, s14, v229
	v_or_b32_e32 v230, 8, v225
	v_xor_b32_e32 v230, v230, v227
	v_lshlrev_b32_e32 v230, 3, v230
	v_lshl_add_u32 v230, v226, 7, v230
	v_add_u32_e32 v230, s14, v230
	v_or_b32_e32 v231, 12, v225
	v_xor_b32_e32 v231, v231, v227
	v_lshlrev_b32_e32 v231, 3, v231
	v_lshl_add_u32 v231, v226, 7, v231
	v_add_u32_e32 v231, s14, v231
	v_add_u32_e32 v233, s13, v236
	v_mul_u32_u24_e32 v233, 0x1a20, v233
	v_lshl_add_u32 v233, v237, 4, v233
	s_lshl_b32 s16, s6, 1
	v_add_u32_e32 v233, s16, v233
	s_add_u32 s16, s94, 0x8748000
	s_addc_u32 s17, s95, 0
	v_cvt_pk_bf16_f32 v6, v6, v7
	v_cvt_pk_bf16_f32 v7, v8, v9
	ds_write_b64 v228, v[6:7] offset:0
	v_cvt_pk_bf16_f32 v34, v34, v35
	v_cvt_pk_bf16_f32 v35, v36, v37
	ds_write_b64 v229, v[34:35] offset:0
	v_cvt_pk_bf16_f32 v38, v38, v39
	v_cvt_pk_bf16_f32 v39, v40, v41
	ds_write_b64 v230, v[38:39] offset:0
	v_cvt_pk_bf16_f32 v30, v30, v31
	v_cvt_pk_bf16_f32 v31, v32, v33
	ds_write_b64 v231, v[30:31] offset:0
	v_cvt_pk_bf16_f32 v42, v42, v43
	v_cvt_pk_bf16_f32 v43, v44, v45
	ds_write_b64 v228, v[42:43] offset:2048
	v_cvt_pk_bf16_f32 v46, v46, v47
	v_cvt_pk_bf16_f32 v47, v48, v49
	ds_write_b64 v229, v[46:47] offset:2048
	v_cvt_pk_bf16_f32 v54, v54, v55
	v_cvt_pk_bf16_f32 v55, v56, v57
	ds_write_b64 v230, v[54:55] offset:2048
	v_cvt_pk_bf16_f32 v26, v26, v27
	v_cvt_pk_bf16_f32 v27, v28, v29
	ds_write_b64 v231, v[26:27] offset:2048
	v_cvt_pk_bf16_f32 v50, v50, v51
	v_cvt_pk_bf16_f32 v51, v52, v53
	ds_write_b64 v228, v[50:51] offset:4096
	v_cvt_pk_bf16_f32 v62, v62, v63
	v_cvt_pk_bf16_f32 v63, v64, v65
	ds_write_b64 v229, v[62:63] offset:4096
	v_cvt_pk_bf16_f32 v58, v58, v59
	v_cvt_pk_bf16_f32 v59, v60, v61
	ds_write_b64 v230, v[58:59] offset:4096
	v_cvt_pk_bf16_f32 v14, v14, v15
	v_cvt_pk_bf16_f32 v15, v16, v17
	ds_write_b64 v231, v[14:15] offset:4096
	v_cvt_pk_bf16_f32 v22, v22, v23
	v_cvt_pk_bf16_f32 v23, v24, v25
	ds_write_b64 v228, v[22:23] offset:6144
	v_cvt_pk_bf16_f32 v18, v18, v19
	v_cvt_pk_bf16_f32 v19, v20, v21
	ds_write_b64 v229, v[18:19] offset:6144
	v_cvt_pk_bf16_f32 v10, v10, v11
	v_cvt_pk_bf16_f32 v11, v12, v13
	ds_write_b64 v230, v[10:11] offset:6144
	v_cvt_pk_bf16_f32 v2, v2, v3
	v_cvt_pk_bf16_f32 v3, v4, v5
	ds_write_b64 v231, v[2:3] offset:6144
	s_waitcnt lgkmcnt(0)
	ds_read_b128 v[66:69], v232 offset:0
	ds_read_b128 v[70:73], v232 offset:1024
	ds_read_b128 v[74:77], v232 offset:2048
	ds_read_b128 v[78:81], v232 offset:3072
	ds_read_b128 v[82:85], v232 offset:4096
	ds_read_b128 v[86:89], v232 offset:5120
	ds_read_b128 v[90:93], v232 offset:6144
	ds_read_b128 v[94:97], v232 offset:7168
	s_waitcnt lgkmcnt(7)
	global_store_dwordx4 v233, v[66:69], s[16:17] sc1
	s_waitcnt lgkmcnt(6)
	v_add_u32_e32 v235, 0xd100, v233
	global_store_dwordx4 v235, v[70:73], s[16:17] sc1
	s_waitcnt lgkmcnt(5)
	v_add_u32_e32 v235, 0x1a200, v233
	global_store_dwordx4 v235, v[74:77], s[16:17] sc1
	s_waitcnt lgkmcnt(4)
	v_add_u32_e32 v235, 0x27300, v233
	global_store_dwordx4 v235, v[78:81], s[16:17] sc1
	s_waitcnt lgkmcnt(3)
	v_add_u32_e32 v235, 0x34400, v233
	global_store_dwordx4 v235, v[82:85], s[16:17] sc1
	s_waitcnt lgkmcnt(2)
	v_add_u32_e32 v235, 0x41500, v233
	global_store_dwordx4 v235, v[86:89], s[16:17] sc1
	s_waitcnt lgkmcnt(1)
	v_add_u32_e32 v235, 0x4e600, v233
	global_store_dwordx4 v235, v[90:93], s[16:17] sc1
	s_waitcnt lgkmcnt(0)
	v_add_u32_e32 v235, 0x5b700, v233
	global_store_dwordx4 v235, v[94:97], s[16:17] sc1
	s_branch .LBB0_345
